# v25 + RS16 panel-scan loops visit only the unit indices that can introduce a new panel key (3 GEMM phase prologues)
# speedup vs baseline: 1.0153x; 1.0029x over previous
;     __device__ __forceinline__ bool next(int i, Unit& u) const { const int j = i / 6; if (!S.next(j, u)) return false; u.kind = i - 6 * j; return true; }
; template <class Epi, class Sched>
; __device__ __forceinline__ void gemm_phase(LAS unsigned char* lds, const Gemm g, const Sched S, const Epi E, const int tid) {
;     ...
;         rc.ssq_x = E.ssq_x; Unit uu;
;         for (int i = 0; S.next(i, uu); ++i) { const int key = Epi::RS16 == 2 ? uu.pn : uu.pm; if (key != rc.p0 && key != rc.p1) { if (rc.p0 < 0) rc.p0 = key; else if (rc.p1 < 0) rc.p1 = key; } }
.LBB0_54:
	s_mul_i32 s6, s94, 5
	s_add_u32 s4, s4, s6
	s_addc_u32 s5, s5, 0
	s_mov_b64 s[6:7], 0

;     __device__ __forceinline__ bool next(int i, Unit& u) const { const int j = i / 6; if (!S.next(j, u)) return false; u.kind = i - 6 * j; return true; }
; template <class Epi, class Sched>
; __device__ __forceinline__ void gemm_phase(LAS unsigned char* lds, const Gemm g, const Sched S, const Epi E, const int tid) {
;     ...
;         rc.ssq_x = E.ssq_x; Unit uu;
;         for (int i = 0; S.next(i, uu); ++i) { const int key = Epi::RS16 == 2 ? uu.pn : uu.pm; if (key != rc.p0 && key != rc.p1) { if (rc.p0 < 0) rc.p0 = key; else if (rc.p1 < 0) rc.p1 = key; } }
.LBB0_532:
	s_lshl_b32 s6, s94, 2
	s_add_u32 s4, s4, s6
	s_addc_u32 s5, s5, 0
	s_mov_b64 s[6:7], 0

;     __device__ __forceinline__ bool next(int i, Unit& u) const { const int j = i / 6; if (!S.next(j, u)) return false; u.kind = i - 6 * j; return true; }
;     __device__ static __forceinline__ bool rs_kind(int kind) { return (kind & 1) == 0; }
; template <class Epi, class Sched, class GSel>
; __device__ __forceinline__ void gemm_multi(LAS unsigned char* lds, const GSel GS, const Sched S, const Epi E, const int tid) {
;     ...
;         for (int i = 0; S.next(i, uu); ++i) { if (!Epi::rs_kind(uu.kind)) continue; const int key = uu.pm; if (key != rc.p0 && key != rc.p1) { if (rc.p0 < 0) rc.p0 = key; else if (rc.p1 < 0) rc.p1 = key; } }
.LBB0_853:
	s_add_i32 s10, s10, 6
	s_mov_b64 s[4:5], 0
